# MoBA and NSA-selected K/V prefetch addresses via SGPR base + loop-invariant VGPR offsets (fewer VALU per step)
# baseline (speedup 1.0000x reference)
.LBB0_867:
	s_or_b64 exec, exec, s[0:1]
	v_lshrrev_b32_e32 v4, 5, v148
	v_lshlrev_b32_e32 v132, 4, v4
	v_mov_b32_e32 v133, v151
	s_waitcnt lgkmcnt(0)
	v_lshl_add_u64 v[2:3], s[86:87], 0, v[132:133]
	s_mov_b64 s[0:1], 0xa800000
	v_lshl_add_u64 v[134:135], v[2:3], 0, s[0:1]
	v_lshl_add_u64 v[2:3], s[86:87], 0, v[150:151]
	s_mov_b64 s[0:1], 0x2700000
	s_lshl_b32 s2, s93, 5
	v_lshl_add_u64 v[136:137], v[2:3], 0, s[0:1]
	s_add_i32 s0, 0, 0x12d00
	v_and_b32_e32 v2, 32, v148
	v_add_u32_e32 v133, s0, v150
	v_add_u32_e32 v155, s0, v2
	s_add_u32 s0, s86, 0xc800000
	v_writelane_b32 v240, s0, 22
	s_addc_u32 s0, s87, 0
	v_writelane_b32 v240, s0, 26
	s_add_u32 s0, s86, 0xe800000
	v_writelane_b32 v240, s0, 34
	s_addc_u32 s0, s87, 0
	v_and_b32_e32 v1, 31, v188
	v_writelane_b32 v240, s0, 35
	s_movk_i32 s0, 0x90
	v_mad_u32_u24 v156, v149, s0, 0
	v_mad_u32_u24 v159, v1, s0, 0
	s_add_u32 s0, s86, 0x6800000
	v_writelane_b32 v240, s0, 36
	s_addc_u32 s0, s87, 0
	v_writelane_b32 v240, s0, 37
	s_lshr_b32 s0, s92, 7
	s_add_u32 s1, s86, 0x8800000
	v_lshlrev_b32_e32 v138, 2, v4
	v_and_b32_e32 v3, 16, v188
	v_writelane_b32 v240, s1, 38
	s_addc_u32 s1, s87, 0
	v_or_b32_e32 v154, s2, v1
	v_and_or_b32 v2, v162, 3, v138
	v_and_or_b32 v3, v150, 12, v3
	v_and_or_b32 v193, s2, 32, v1
	s_add_u32 s2, s86, 0x3200000
	v_mul_u32_u24_e32 v2, 0xc0, v2
	v_lshlrev_b32_e32 v3, 1, v3
	v_writelane_b32 v240, s1, 39
	s_addc_u32 s3, s87, 0
	v_add3_u32 v160, 0, v2, v3
	v_writelane_b32 v240, s2, 40
	v_add_u32_e32 v2, 0x200, v188
	v_lshlrev_b32_e32 v140, 4, v2
	v_writelane_b32 v240, s3, 41
	v_lshrrev_b32_e32 v2, 3, v2
	v_lshlrev_b32_e32 v0, 3, v4
	v_mul_u32_u24_e32 v4, 0x90, v2
	v_mul_u32_u24_e32 v7, 0xc0, v2
	v_writelane_b32 v240, s0, 42
	v_lshl_or_b32 v2, s0, 6, v193
	s_movk_i32 s0, 0x84
	v_mul_lo_u32 v2, v2, s0
	v_add3_u32 v194, 0, v2, v138
	s_add_i32 s0, 0, 0x13540
	v_and_b32_e32 v2, 7, v188
	v_add_u32_e32 v195, s0, v150
	v_cmp_eq_u32_e64 s[0:1], 0, v2
	v_cmp_eq_u32_e64 s[6:7], 0, v153
	v_mov_b32_e32 v153, v151
	v_writelane_b32 v240, s0, 43
	v_mul_u32_u24_e32 v3, 0x84, v149
	v_lshlrev_b32_e32 v8, 4, v2
	v_writelane_b32 v240, s1, 44
	v_cmp_ne_u32_e64 s[0:1], 0, v2
	v_lshlrev_b32_e32 v196, 2, v2
	v_add3_u32 v197, 0, v3, v8
	v_writelane_b32 v240, s0, 45
	v_lshl_add_u64 v[2:3], s[86:87], 0, v[152:153]
	v_and_b32_e32 v157, 0x70, v152
	v_writelane_b32 v240, s1, 46
	s_add_i32 s0, 0, 0x12c00
	v_lshl_add_u32 v202, v149, 2, s0
	v_lshl_add_u32 v203, v193, 2, s0
	s_add_u32 s0, s86, 0x11800000
	v_writelane_b32 v240, s0, 47
	s_addc_u32 s0, s87, 0
	v_writelane_b32 v240, s0, 48
	s_add_u32 s0, s86, 0x12000000
	v_writelane_b32 v240, s0, 49
	s_addc_u32 s0, s87, 0
	v_writelane_b32 v240, s0, 50
	s_add_u32 s0, s86, 0x12800000
	v_writelane_b32 v240, s0, 51
	s_addc_u32 s0, s87, 0
	v_writelane_b32 v240, s0, 52
	s_add_u32 s0, s86, 0x13000000
	v_writelane_b32 v240, s0, 53
	s_addc_u32 s0, s87, 0
	v_writelane_b32 v240, s0, 54
	s_add_u32 s0, s86, 0x4800000
	s_addc_u32 s1, s87, 0
	v_writelane_b32 v240, s0, 55
	v_mul_u32_u24_e32 v5, 0x90, v149
	v_mul_u32_u24_e32 v6, 0xc0, v149
	v_writelane_b32 v240, s1, 56
	s_mov_b64 s[0:1], 0xe806000
	v_lshl_add_u64 v[142:143], v[2:3], 0, s[0:1]
	s_mov_b64 s[0:1], 0x12006000
	v_lshl_add_u64 v[144:145], v[2:3], 0, s[0:1]
	v_add_u32_e32 v241, 0x800000, v152
	v_add_u32_e32 v242, 0x2000, v152
	v_add_u32_e32 v243, 0x802000, v152
	s_mov_b64 s[0:1], 0
	v_add_u32_e32 v1, 0, v157
	v_writelane_b32 v240, s0, 16
	v_lshlrev_b32_e32 v150, 1, v0
	v_mbcnt_lo_u32_b32 v0, -1, 0
	s_mov_b32 s97, 0
	v_mad_u32_u24 v158, v149, 48, v156
	v_or_b32_e32 v161, 32, v138
	v_or_b32_e32 v162, 33, v138
	v_or_b32_e32 v163, 2, v138
	v_or_b32_e32 v164, 34, v138
	v_or_b32_e32 v165, 3, v138
	v_or_b32_e32 v166, 35, v138
	v_or_b32_e32 v167, 8, v138
	v_or_b32_e32 v168, 40, v138
	v_or_b32_e32 v169, 9, v138
	v_or_b32_e32 v170, 41, v138
	v_or_b32_e32 v171, 10, v138
	v_or_b32_e32 v172, 42, v138
	v_or_b32_e32 v173, 11, v138
	v_or_b32_e32 v174, 43, v138
	v_or_b32_e32 v175, 16, v138
	v_or_b32_e32 v176, 48, v138
	v_or_b32_e32 v177, 17, v138
	v_or_b32_e32 v178, 49, v138
	v_or_b32_e32 v179, 18, v138
	v_or_b32_e32 v180, 50, v138
	v_or_b32_e32 v181, 19, v138
	v_or_b32_e32 v182, 51, v138
	v_or_b32_e32 v183, 24, v138
	v_or_b32_e32 v184, 56, v138
	v_or_b32_e32 v185, 25, v138
	v_or_b32_e32 v186, 57, v138
	v_or_b32_e32 v187, 26, v138
	v_or_b32_e32 v189, 58, v138
	v_or_b32_e32 v190, 27, v138
	v_or_b32_e32 v191, 59, v138
	v_subrev_u32_e32 v192, 64, v154
	v_mov_b32_e32 v141, v151
	v_cmp_gt_u32_e64 s[8:9], 32, v148
	v_add_u32_e32 v198, 0xa800, v197
	v_or_b32_e32 v199, 1, v196
	v_or_b32_e32 v200, 2, v196
	v_or_b32_e32 v201, 3, v196
	v_or_b32_e32 v204, 1, v138
	v_add_u32_e32 v205, 1, v193
	v_writelane_b32 v240, s1, 17
	s_add_i32 s14, 0, 0x13500
	s_mov_b32 s33, 0xff800000
	s_mov_b32 s92, 0x41000000
	s_mov_b64 s[10:11], 0x4000
	v_add_u32_e32 v206, v1, v5
	v_add_u32_e32 v207, v1, v6
	v_add_u32_e32 v208, v1, v4
	v_add_u32_e32 v209, v1, v7
	v_mov_b32_e32 v210, 0xff800000
	v_mbcnt_hi_u32_b32 v211, -1, v0
	v_writelane_b32 v240, s14, 15
	s_branch .LBB0_872

.LBB0_906:
	s_lshl_b64 s[4:5], s[0:1], 18
	v_readlane_b32 s1, v240, 22
	s_add_u32 s2, s1, s4
	v_readlane_b32 s1, v240, 26
	s_addc_u32 s3, s1, s5
	v_readlane_b32 s1, v240, 34
	s_add_u32 s12, s1, s4
	v_readlane_b32 s1, v240, 35
	s_addc_u32 s13, s1, s5
	v_lshl_add_u64 v[0:1], s[2:3], 0, v[152:153]
	s_movk_i32 s1, 0x2000
	v_lshl_add_u64 v[2:3], s[12:13], 0, v[152:153]
	s_add_u32 s98, s2, 0x4000
	s_addc_u32 s99, s3, 0
	s_add_u32 s100, s12, 0x4000
	s_addc_u32 s101, s13, 0
	global_load_dwordx4 v[96:99], v[0:1], off
	global_load_dwordx4 v[100:103], v[2:3], off
	v_add_co_u32_e32 v0, vcc, s1, v0
	v_mov_b32_e32 v14, v151
	s_nop 0
	v_addc_co_u32_e32 v1, vcc, 0, v1, vcc
	v_add_co_u32_e32 v2, vcc, s1, v2
	v_mov_b32_e32 v15, v151
	s_nop 0
	v_addc_co_u32_e32 v3, vcc, 0, v3, vcc
	global_load_dwordx4 v[104:107], v[0:1], off
	global_load_dwordx4 v[108:111], v[2:3], off
	s_lshl_b32 s1, s93, 2
	v_mov_b32_e32 v0, v151
	v_mov_b32_e32 v1, v151
	v_mov_b32_e32 v2, v151
	v_mov_b32_e32 v3, v151
	v_mov_b32_e32 v4, v151
	v_mov_b32_e32 v5, v151
	v_mov_b32_e32 v6, v151
	v_mov_b32_e32 v7, v151
	v_mov_b32_e32 v8, v151
	v_mov_b32_e32 v9, v151
	v_mov_b32_e32 v10, v151
	v_mov_b32_e32 v11, v151
	v_mov_b32_e32 v12, v151
	v_mov_b32_e32 v13, v151
	v_mov_b64_e32 v[30:31], v[14:15]
	v_mov_b64_e32 v[46:47], v[14:15]
	s_or_b32 s2, s1, 3
	s_mov_b32 s3, 0
	v_lshl_add_u64 v[130:131], v[142:143], 0, s[4:5]
	v_mov_b32_e32 v147, 0
	v_mov_b32_e32 v148, 0
	v_mov_b64_e32 v[28:29], v[12:13]
	v_mov_b64_e32 v[26:27], v[10:11]
	v_mov_b64_e32 v[24:25], v[8:9]
	v_mov_b64_e32 v[22:23], v[6:7]
	v_mov_b64_e32 v[20:21], v[4:5]
	v_mov_b64_e32 v[18:19], v[2:3]
	v_mov_b64_e32 v[16:17], v[0:1]
	v_mov_b64_e32 v[44:45], v[12:13]
	v_mov_b64_e32 v[42:43], v[10:11]
	v_mov_b64_e32 v[40:41], v[8:9]
	v_mov_b64_e32 v[38:39], v[6:7]
	v_mov_b64_e32 v[36:37], v[4:5]
	v_mov_b64_e32 v[34:35], v[2:3]
	v_mov_b64_e32 v[32:33], v[0:1]
	s_mov_b32 s13, 0
.LBB0_907:
	v_add_u32_e32 v149, v156, v157
	v_add_u32_e32 v212, v158, v157
	s_waitcnt vmcnt(2)
	ds_write_b128 v149, v[96:99]
	ds_write_b128 v212, v[100:103] offset:18432
	s_add_i32 s12, s13, 2
	s_waitcnt lgkmcnt(0)
	s_barrier
	s_cmp_gt_i32 s12, s2
	s_cselect_b64 s[48:49], -1, 0
	s_and_b64 vcc, exec, s[48:49]
	s_cbranch_vccnz .LBB0_909
	global_load_dwordx4 v[96:99], v152, s[98:99]
	global_load_dwordx4 v[100:103], v152, s[100:101]
	s_add_u32 s98, s98, 0x2000
	s_addc_u32 s99, s99, 0
	s_add_u32 s100, s100, 0x2000
	s_addc_u32 s101, s101, 0

.Lmoba_odd_ok:
	ds_write_b128 v149, v[104:107] offset:9216
	ds_write_b128 v212, v[108:111] offset:30720
	s_waitcnt lgkmcnt(0)
	s_barrier
	s_cmp_gt_i32 s13, s1
	s_cbranch_scc1 .LBB0_924
	global_load_dwordx4 v[104:107], v152, s[98:99]
	global_load_dwordx4 v[108:111], v152, s[100:101]
	s_add_u32 s98, s98, 0x2000
	s_addc_u32 s99, s99, 0
	s_add_u32 s100, s100, 0x2000
	s_addc_u32 s101, s101, 0

.LBB0_936:
	s_andn2_b64 vcc, exec, s[48:49]
	s_addk_i32 s3, 0x80
	s_cbranch_vccz .LBB0_938
	s_mov_b32 s13, s12
	s_branch .LBB0_907

.LBB0_1006:
	s_mov_b64 s[4:5], exec
	v_readlane_b32 s2, v240, 43
	v_readlane_b32 s3, v240, 44
	s_and_b64 s[2:3], s[4:5], s[2:3]
	s_mov_b64 exec, s[2:3]
	ds_write_b32 v202, v0
	s_or_b64 exec, exec, s[4:5]
	s_lshl_b64 s[50:51], s[0:1], 18
	v_readlane_b32 s1, v240, 47
	s_add_u32 s2, s1, s50
	v_readlane_b32 s1, v240, 48
	s_addc_u32 s3, s1, s51
	s_add_u32 s100, s2, 0x4000
	s_addc_u32 s101, s3, 0
	v_readlane_b32 s1, v240, 49
	s_add_u32 s4, s1, s50
	v_readlane_b32 s1, v240, 50
	s_addc_u32 s5, s1, s51
	v_lshl_add_u64 v[0:1], s[4:5], 0, v[152:153]
	s_waitcnt lgkmcnt(0)
	s_barrier
	v_lshl_add_u64 v[2:3], s[2:3], 0, v[152:153]
	s_waitcnt vmcnt(0)
	v_mov_b64_e32 v[100:101], v[220:221]
	v_mov_b64_e32 v[102:103], v[222:223]
	v_mov_b64_e32 v[96:97], v[216:217]
	v_mov_b64_e32 v[98:99], v[218:219]
	ds_read_b32 v128, v203
	s_cmp_lt_i32 s93, 1
	s_cbranch_scc1 .LBB0_1010
	v_add_co_u32_e32 v2, vcc, 0x2000, v2
	s_nop 1
	v_addc_co_u32_e32 v3, vcc, 0, v3, vcc
	v_add_co_u32_e32 v0, vcc, 0x2000, v0
	s_nop 1
	v_addc_co_u32_e32 v1, vcc, 0, v1, vcc
	v_mov_b64_e32 v[104:105], v[224:225]
	v_mov_b64_e32 v[106:107], v[226:227]
	v_mov_b64_e32 v[108:109], v[228:229]
	v_mov_b64_e32 v[110:111], v[230:231]
.LBB0_1010:
	v_mov_b32_e32 v16, v151
	v_mov_b32_e32 v17, v151
	v_mov_b32_e32 v30, v151
	v_mov_b32_e32 v31, v151
	v_mov_b32_e32 v18, v151
	v_mov_b32_e32 v19, v151
	v_mov_b32_e32 v20, v151
	v_mov_b32_e32 v21, v151
	v_mov_b32_e32 v22, v151
	v_mov_b32_e32 v23, v151
	v_mov_b32_e32 v24, v151
	v_mov_b32_e32 v25, v151
	v_mov_b32_e32 v26, v151
	v_mov_b32_e32 v27, v151
	v_mov_b32_e32 v28, v151
	v_mov_b32_e32 v29, v151
	v_mov_b64_e32 v[0:1], v[16:17]
	v_mov_b64_e32 v[46:47], v[30:31]
	s_sub_i32 s1, 0, s93
	v_mov_b32_e32 v215, 0
	s_mov_b32 s2, 3
	v_mov_b32_e32 v214, 0
	v_mov_b64_e32 v[2:3], v[18:19]
	v_mov_b64_e32 v[4:5], v[20:21]
	v_mov_b64_e32 v[6:7], v[22:23]
	v_mov_b64_e32 v[8:9], v[24:25]
	v_mov_b64_e32 v[10:11], v[26:27]
	v_mov_b64_e32 v[12:13], v[28:29]
	v_mov_b64_e32 v[14:15], v[30:31]
	v_mov_b64_e32 v[44:45], v[28:29]
	v_mov_b64_e32 v[42:43], v[26:27]
	v_mov_b64_e32 v[40:41], v[24:25]
	v_mov_b64_e32 v[38:39], v[22:23]
	v_mov_b64_e32 v[36:37], v[20:21]
	v_mov_b64_e32 v[34:35], v[18:19]
	v_mov_b64_e32 v[32:33], v[16:17]
	s_branch .LBB0_1013

.LBB0_1012:
	s_add_i32 s2, s2, 2
	s_add_u32 s100, s100, 0x4000
	s_addc_u32 s101, s101, 0
	s_cmp_le_i32 s3, s93
	s_cbranch_scc0 .LBB0_1033

.Lsel_even_ok:
	ds_write_b128 v212, v[96:99]
	ds_write_b128 v213, v[100:103] offset:18432
	s_waitcnt lgkmcnt(0)
	s_barrier
	s_add_i32 s3, s2, -1
	s_cmp_gt_i32 s3, s93
	s_cbranch_scc1 .LBB0_1015
	global_load_dwordx4 v[96:99], v152, s[100:101]
	global_load_dwordx4 v[100:103], v241, s[100:101]

.Lsel_odd_ok:
	ds_write_b128 v212, v[104:107] offset:9216
	ds_write_b128 v213, v[108:111] offset:30720
	s_waitcnt lgkmcnt(0)
	s_barrier
	s_cmp_gt_i32 s2, s93
	s_cbranch_scc1 .LBB0_1026
	global_load_dwordx4 v[104:107], v242, s[100:101]
	global_load_dwordx4 v[108:111], v243, s[100:101]
